# position-DFT tile epilogue: 8 columns per lane, 16-byte write-through stores
# speedup vs baseline: 1.1121x; 1.0010x over previous
; DI u32x2 pack4(f32x4 v) { u32x2 r = {cvtpk(v[0], v[1]), cvtpk(v[2], v[3])}; return r; }
;     ...
;   __syncthreads();
; #pragma unroll 4
;   for (int it = 0; it < 16; ++it) {
;     const int idx = it * 256 + tid; const int row = idx >> 5, c4 = (idx & 31) * 4;
;     f32x4 v = *(const f32x4*)(ct + row * 132 + c4);
;     epi(row, c4, v);
;   }
;   __syncthreads();
; DI void phase_mix(KP p, int l, char* lds) {
;     ...
;       bf16_t* yo = YD + rbase * 256 + nt * 128;
;       gemm_tile(Ap, K, Bp, K, K, lds, [&](int m, int n, f32x4 v) {
;         f32x4 o = {v[0] * sc, v[1] * sc, v[2] * sc, v[3] * sc};
;         *(u32x2*)(yo + (size_t)m * 256 + n) = pack4(o); });
;       asm volatile("s_waitcnt vmcnt(0)" ::: "memory");
;       __syncthreads();
;       if (tid0 == 0) {
;         __builtin_amdgcn_fence(__ATOMIC_RELEASE, "agent");
;         asm volatile("s_waitcnt vmcnt(0)" ::: "memory");
;         __hip_atomic_fetch_add(&cnt[b * 18 + (isl ? mt : 16 + mt)], 1u, __ATOMIC_RELAXED, __HIP_MEMORY_SCOPE_AGENT);
;       }
.LBB0_176:
	v_and_b32_e32 v0, 64, v82
	v_lshl_add_u32 v0, v0, 2, v85
	v_lshlrev_b32_e32 v66, 4, v94
	v_mul_u32_u24_e32 v67, 0x210, v95
	v_add3_u32 v0, v0, v66, v67
	ds_write_b128 v0, v[50:53]
	ds_write_b128 v0, v[54:57] offset:32
	ds_write_b128 v0, v[58:61] offset:64
	ds_write_b128 v0, v[62:65] offset:96
	ds_write_b128 v0, v[34:37] offset:128
	ds_write_b128 v0, v[38:41] offset:160
	ds_write_b128 v0, v[42:45] offset:192
	ds_write_b128 v0, v[46:49] offset:224
	ds_write_b128 v0, v[18:21] offset:16896
	ds_write_b128 v0, v[22:25] offset:16928
	ds_write_b128 v0, v[26:29] offset:16960
	ds_write_b128 v0, v[30:33] offset:16992
	ds_write_b128 v0, v[2:5] offset:17024
	ds_write_b128 v0, v[6:9] offset:17056
	ds_write_b128 v0, v[10:13] offset:17088
	ds_write_b128 v0, v[14:17] offset:17120
	v_and_b32_e32 v0, 0xe0, v82
	s_lshl_b64 s[18:19], s[50:51], 9
	v_lshlrev_b32_e32 v0, 4, v0
	v_lshl_add_u64 v[2:3], s[18:19], 0, v[0:1]
	v_mov_b32_e32 v0, 5
	v_readlane_b32 s18, v255, 45
	v_lshrrev_b32_sdwa v0, v0, v82 dst_sel:DWORD dst_unused:UNUSED_PAD src0_sel:DWORD src1_sel:BYTE_0
	s_movk_i32 s2, 0x210
	v_lshl_or_b32 v2, v84, 3, v2
	v_readlane_b32 s19, v255, 46
	v_mad_u32_u24 v0, v0, s2, v83
	v_lshlrev_b32_e32 v4, 4, v84
	s_mov_b32 s41, s40
	v_lshl_add_u64 v[2:3], s[18:19], 0, v[2:3]
	v_add3_u32 v0, v0, v4, 0
	s_mov_b64 s[50:51], 0
	s_waitcnt lgkmcnt(0)
	s_barrier
	v_and_b32_e32 v86, 0xff, v82
	v_lshrrev_b32_e32 v87, 4, v86
	v_and_b32_e32 v88, 15, v86
	s_movk_i32 s5, 0x210
	v_mad_u32_u24 v89, v87, s5, v83
	v_lshl_add_u32 v89, v88, 5, v89
	v_lshlrev_b32_e32 v90, 9, v87
	v_lshl_add_u32 v90, v88, 4, v90
	v_and_b32_e32 v91, 0xe0, v82
	v_lshlrev_b32_e32 v91, 4, v91
	v_lshl_or_b32 v91, v84, 3, v91
	v_sub_u32_e32 v90, v90, v91
	v_ashrrev_i32_e32 v91, 31, v90
	v_lshl_add_u64 v[92:93], v[90:91], 0, v[2:3]
	v_add_co_u32_e32 v92, vcc, 0x14f75100, v92
	s_nop 1
	v_addc_co_u32_e32 v93, vcc, 0, v93, vcc
	s_mov_b64 s[52:53], 0x2000
	ds_read_b128 v[34:37], v89 offset:0
	ds_read_b128 v[38:41], v89 offset:16
	ds_read_b128 v[42:45], v89 offset:8448
	ds_read_b128 v[46:49], v89 offset:8464
	ds_read_b128 v[50:53], v89 offset:16896
	ds_read_b128 v[54:57], v89 offset:16912
	ds_read_b128 v[58:61], v89 offset:25344
	ds_read_b128 v[62:65], v89 offset:25360
	s_waitcnt lgkmcnt(6)
	v_pk_mul_f32 v[34:35], s[40:41], v[34:35]
	v_pk_mul_f32 v[36:37], s[40:41], v[36:37]
	v_pk_mul_f32 v[38:39], s[40:41], v[38:39]
	v_pk_mul_f32 v[40:41], s[40:41], v[40:41]
	v_cvt_pk_bf16_f32 v34, v34, v35
	v_cvt_pk_bf16_f32 v35, v36, v37
	v_cvt_pk_bf16_f32 v36, v38, v39
	v_cvt_pk_bf16_f32 v37, v40, v41
	global_store_dwordx4 v[92:93], v[34:37], off sc0 sc1
	v_lshl_add_u64 v[92:93], v[92:93], 0, s[52:53]
	s_waitcnt lgkmcnt(4)
	v_pk_mul_f32 v[42:43], s[40:41], v[42:43]
	v_pk_mul_f32 v[44:45], s[40:41], v[44:45]
	v_pk_mul_f32 v[46:47], s[40:41], v[46:47]
	v_pk_mul_f32 v[48:49], s[40:41], v[48:49]
	v_cvt_pk_bf16_f32 v42, v42, v43
	v_cvt_pk_bf16_f32 v43, v44, v45
	v_cvt_pk_bf16_f32 v44, v46, v47
	v_cvt_pk_bf16_f32 v45, v48, v49
	global_store_dwordx4 v[92:93], v[42:45], off sc0 sc1
	v_lshl_add_u64 v[92:93], v[92:93], 0, s[52:53]
	s_waitcnt lgkmcnt(2)
	v_pk_mul_f32 v[50:51], s[40:41], v[50:51]
	v_pk_mul_f32 v[52:53], s[40:41], v[52:53]
	v_pk_mul_f32 v[54:55], s[40:41], v[54:55]
	v_pk_mul_f32 v[56:57], s[40:41], v[56:57]
	v_cvt_pk_bf16_f32 v50, v50, v51
	v_cvt_pk_bf16_f32 v51, v52, v53
	v_cvt_pk_bf16_f32 v52, v54, v55
	v_cvt_pk_bf16_f32 v53, v56, v57
	global_store_dwordx4 v[92:93], v[50:53], off sc0 sc1
	v_lshl_add_u64 v[92:93], v[92:93], 0, s[52:53]
	s_waitcnt lgkmcnt(0)
	v_pk_mul_f32 v[58:59], s[40:41], v[58:59]
	v_pk_mul_f32 v[60:61], s[40:41], v[60:61]
	v_pk_mul_f32 v[62:63], s[40:41], v[62:63]
	v_pk_mul_f32 v[64:65], s[40:41], v[64:65]
	v_cvt_pk_bf16_f32 v58, v58, v59
	v_cvt_pk_bf16_f32 v59, v60, v61
	v_cvt_pk_bf16_f32 v60, v62, v63
	v_cvt_pk_bf16_f32 v61, v64, v65
	global_store_dwordx4 v[92:93], v[58:61], off sc0 sc1
	v_lshl_add_u64 v[92:93], v[92:93], 0, s[52:53]
	ds_read_b128 v[34:37], v89 offset:33792
	ds_read_b128 v[38:41], v89 offset:33808
	ds_read_b128 v[42:45], v89 offset:42240
	ds_read_b128 v[46:49], v89 offset:42256
	ds_read_b128 v[50:53], v89 offset:50688
	ds_read_b128 v[54:57], v89 offset:50704
	ds_read_b128 v[58:61], v89 offset:59136
	ds_read_b128 v[62:65], v89 offset:59152
	s_waitcnt lgkmcnt(6)
	v_pk_mul_f32 v[34:35], s[40:41], v[34:35]
	v_pk_mul_f32 v[36:37], s[40:41], v[36:37]
	v_pk_mul_f32 v[38:39], s[40:41], v[38:39]
	v_pk_mul_f32 v[40:41], s[40:41], v[40:41]
	v_cvt_pk_bf16_f32 v34, v34, v35
	v_cvt_pk_bf16_f32 v35, v36, v37
	v_cvt_pk_bf16_f32 v36, v38, v39
	v_cvt_pk_bf16_f32 v37, v40, v41
	global_store_dwordx4 v[92:93], v[34:37], off sc0 sc1
	v_lshl_add_u64 v[92:93], v[92:93], 0, s[52:53]
	s_waitcnt lgkmcnt(4)
	v_pk_mul_f32 v[42:43], s[40:41], v[42:43]
	v_pk_mul_f32 v[44:45], s[40:41], v[44:45]
	v_pk_mul_f32 v[46:47], s[40:41], v[46:47]
	v_pk_mul_f32 v[48:49], s[40:41], v[48:49]
	v_cvt_pk_bf16_f32 v42, v42, v43
	v_cvt_pk_bf16_f32 v43, v44, v45
	v_cvt_pk_bf16_f32 v44, v46, v47
	v_cvt_pk_bf16_f32 v45, v48, v49
	global_store_dwordx4 v[92:93], v[42:45], off sc0 sc1
	v_lshl_add_u64 v[92:93], v[92:93], 0, s[52:53]
	s_waitcnt lgkmcnt(2)
	v_pk_mul_f32 v[50:51], s[40:41], v[50:51]
	v_pk_mul_f32 v[52:53], s[40:41], v[52:53]
	v_pk_mul_f32 v[54:55], s[40:41], v[54:55]
	v_pk_mul_f32 v[56:57], s[40:41], v[56:57]
	v_cvt_pk_bf16_f32 v50, v50, v51
	v_cvt_pk_bf16_f32 v51, v52, v53
	v_cvt_pk_bf16_f32 v52, v54, v55
	v_cvt_pk_bf16_f32 v53, v56, v57
	global_store_dwordx4 v[92:93], v[50:53], off sc0 sc1
	v_lshl_add_u64 v[92:93], v[92:93], 0, s[52:53]
	s_waitcnt lgkmcnt(0)
	v_pk_mul_f32 v[58:59], s[40:41], v[58:59]
	v_pk_mul_f32 v[60:61], s[40:41], v[60:61]
	v_pk_mul_f32 v[62:63], s[40:41], v[62:63]
	v_pk_mul_f32 v[64:65], s[40:41], v[64:65]
	v_cvt_pk_bf16_f32 v58, v58, v59
	v_cvt_pk_bf16_f32 v59, v60, v61
	v_cvt_pk_bf16_f32 v60, v62, v63
	v_cvt_pk_bf16_f32 v61, v64, v65
	global_store_dwordx4 v[92:93], v[58:61], off sc0 sc1
	v_lshl_add_u64 v[92:93], v[92:93], 0, s[52:53]
	s_mov_b64 s[50:51], 0x10000
	s_waitcnt lgkmcnt(0)
	s_barrier
	s_waitcnt vmcnt(0)
	s_barrier
	s_and_saveexec_b64 s[18:19], s[64:65]
	s_cbranch_execz .LBB0_125
	s_or_b32 s20, s34, 16
	s_mul_i32 s2, s4, 18
	s_and_b64 s[4:5], s[36:37], exec
	s_cselect_b32 s4, s34, s20
	s_add_i32 s4, s2, s4
	s_ashr_i32 s5, s4, 31
	s_lshl_b64 s[4:5], s[4:5], 2
	v_readlane_b32 s2, v255, 43
	s_add_u32 s4, s2, s4
	v_readlane_b32 s2, v255, 44
	s_addc_u32 s5, s2, s5
	s_waitcnt vmcnt(0)
	v_mov_b64_e32 v[2:3], s[4:5]
	global_atomic_add v[2:3], v197, off
	s_branch .LBB0_125
